# w_down transposition moved on to the up-proj copy workgroups (after the copy queue drains); w_up stays with the idle out-proj workgroups
# speedup vs baseline: 1.4451x; 1.0045x over previous
.LBB0_1105:
	s_load_dword s3, s[0:1], 0xa8
	s_mov_b64 s[4:5], -1
	s_waitcnt lgkmcnt(0)
	s_addk_i32 s3, 0xffb0
	s_cmp_lt_i32 s2, s3
	s_cbranch_scc1 .LBB0_1127
	s_cmpk_lt_i32 s2, 0xf0
	s_cbranch_scc0 .Lwt_skip
	s_load_dwordx2 s[18:19], s[0:1], 0x68
	s_load_dwordx2 s[20:21], s[0:1], 0x60
	s_load_dwordx2 s[22:23], s[0:1], 0x80
	s_mov_b64 exec, -1
	s_sub_i32 s24, s2, 0xb0
	s_addk_i32 s24, 0x840
	v_lshrrev_b32_e32 v40, 5, v156
	v_and_b32_e32 v41, 31, v156
	v_lshlrev_b32_e32 v41, 4, v41
	v_mul_u32_u24_e32 v42, 0x204, v40
	v_add_u32_e32 v42, v42, v41
	v_and_b32_e32 v43, 7, v156
	v_mul_u32_u24_e32 v43, 0x1020, v43
	v_lshrrev_b32_e32 v51, 3, v156
	v_lshl_add_u32 v43, v51, 2, v43
	v_lshrrev_b32_e32 v44, 4, v51
	v_lshlrev_b32_e32 v44, 1, v44
	v_bfe_u32 v52, v156, 2, 1
	v_add_u32_e32 v44, v44, v52
	v_lshlrev_b32_e32 v44, 10, v44
	v_and_b32_e32 v52, 15, v51
	v_lshlrev_b32_e32 v52, 6, v52
	v_and_b32_e32 v53, 3, v156
	v_lshl_add_u32 v52, v53, 4, v52
	v_and_b32_e32 v53, 8, v51
	v_lshlrev_b32_e32 v53, 2, v53
	v_xor_b32_e32 v52, v52, v53
	v_add_u32_e32 v44, v44, v52
	v_add_u32_e32 v45, 0x2000, v44
	v_lshlrev_b32_e32 v50, 2, v40
	s_waitcnt lgkmcnt(0)
	s_cmpk_lt_i32 s24, 0x1340
	s_cbranch_scc0 .Lwt_down_p
	s_sub_i32 s25, s24, 0x840
	s_and_b32 s26, s25, 31
	s_lshr_b32 s27, s25, 5
	s_lshl_b32 s28, s26, 6
	s_and_b32 s29, s27, 1
	s_mul_i32 s29, s29, 0x1600
	s_lshr_b32 s30, s27, 1
	s_lshl_b32 s30, s30, 7
	s_add_i32 s29, s29, s30
	s_mul_i32 s30, s28, 0x2c00
	s_add_i32 s30, s30, s29
	s_lshl_b32 s30, s30, 2
	s_add_u32 s34, s18, s30
	s_addc_u32 s35, s19, 0
	s_lshl_b32 s31, s27, 5
	s_add_i32 s31, s31, s26
	s_mov_b32 s33, 0xb000
	s_mov_b32 s46, 1
	s_mov_b32 s30, 0x2100000
	s_branch .Lwt_dec_p

.Lwt_loop:
	s_addk_i32 s24, 0x40
	s_cmpk_lt_i32 s24, 0x1340
	s_cbranch_scc0 .Lwt_lastB
	s_cmpk_lt_i32 s24, 0x1340
	s_cbranch_scc0 .Lwt_down_r
	s_sub_i32 s25, s24, 0x840
	s_and_b32 s26, s25, 31
	s_lshr_b32 s27, s25, 5
	s_lshl_b32 s28, s26, 6
	s_and_b32 s29, s27, 1
	s_mul_i32 s29, s29, 0x1600
	s_lshr_b32 s30, s27, 1
	s_lshl_b32 s30, s30, 7
	s_add_i32 s29, s29, s30
	s_mul_i32 s30, s28, 0x2c00
	s_add_i32 s30, s30, s29
	s_lshl_b32 s30, s30, 2
	s_add_u32 s34, s18, s30
	s_addc_u32 s35, s19, 0
	s_lshl_b32 s31, s27, 5
	s_add_i32 s31, s31, s26
	s_mov_b32 s33, 0xb000
	s_mov_b32 s46, 1
	s_mov_b32 s30, 0x2100000
	s_branch .Lwt_dec_r

.Lwt_nog_b1:
	ds_write_b32 v42, v20
	ds_write_b32 v42, v21 offset:4
	ds_write_b32 v42, v22 offset:8
	ds_write_b32 v42, v23 offset:12
	ds_write_b32 v42, v24 offset:8256
	ds_write_b32 v42, v25 offset:8260
	ds_write_b32 v42, v26 offset:8264
	ds_write_b32 v42, v27 offset:8268
	ds_write_b32 v42, v28 offset:16512
	ds_write_b32 v42, v29 offset:16516
	ds_write_b32 v42, v30 offset:16520
	ds_write_b32 v42, v31 offset:16524
	ds_write_b32 v42, v32 offset:24768
	ds_write_b32 v42, v33 offset:24772
	ds_write_b32 v42, v34 offset:24776
	ds_write_b32 v42, v35 offset:24780
	s_waitcnt lgkmcnt(0)
	s_barrier
	ds_read_b32 v54, v43
	ds_read_b32 v55, v43 offset:516
	ds_read_b32 v56, v43 offset:1032
	ds_read_b32 v57, v43 offset:1548
	ds_read_b32 v58, v43 offset:2064
	ds_read_b32 v59, v43 offset:2580
	ds_read_b32 v60, v43 offset:3096
	ds_read_b32 v61, v43 offset:3612
	ds_read_b32 v62, v43 offset:256
	ds_read_b32 v63, v43 offset:772
	ds_read_b32 v64, v43 offset:1288
	ds_read_b32 v65, v43 offset:1804
	ds_read_b32 v66, v43 offset:2320
	ds_read_b32 v67, v43 offset:2836
	ds_read_b32 v68, v43 offset:3352
	ds_read_b32 v69, v43 offset:3868
	s_waitcnt lgkmcnt(0)
	v_cvt_pk_bf16_f32 v72, v54, v55
	v_cvt_pk_bf16_f32 v73, v56, v57
	v_cvt_pk_bf16_f32 v74, v58, v59
	v_cvt_pk_bf16_f32 v75, v60, v61
	v_cvt_pk_bf16_f32 v76, v62, v63
	v_cvt_pk_bf16_f32 v77, v64, v65
	v_cvt_pk_bf16_f32 v78, v66, v67
	v_cvt_pk_bf16_f32 v79, v68, v69
	global_store_dwordx4 v44, v[72:75], s[48:49]
	global_store_dwordx4 v45, v[76:79], s[48:49]
	s_barrier
	s_addk_i32 s24, 0x40
	s_cmpk_lt_i32 s24, 0x1340
	s_cbranch_scc0 .Lwt_lastA
	s_cmpk_lt_i32 s24, 0x1340
	s_cbranch_scc0 .Lwt_down_s
	s_sub_i32 s25, s24, 0x840
	s_and_b32 s26, s25, 31
	s_lshr_b32 s27, s25, 5
	s_lshl_b32 s28, s26, 6
	s_and_b32 s29, s27, 1
	s_mul_i32 s29, s29, 0x1600
	s_lshr_b32 s30, s27, 1
	s_lshl_b32 s30, s30, 7
	s_add_i32 s29, s29, s30
	s_mul_i32 s30, s28, 0x2c00
	s_add_i32 s30, s30, s29
	s_lshl_b32 s30, s30, 2
	s_add_u32 s34, s18, s30
	s_addc_u32 s35, s19, 0
	s_lshl_b32 s31, s27, 5
	s_add_i32 s31, s31, s26
	s_mov_b32 s33, 0xb000
	s_mov_b32 s47, 1
	s_mov_b32 s30, 0x2100000
	s_branch .Lwt_dec_s

.LBB0_1293:
	s_load_dwordx2 s[18:19], s[0:1], 0x68
	s_load_dwordx2 s[20:21], s[0:1], 0x60
	s_load_dwordx2 s[22:23], s[0:1], 0x80
	s_mov_b64 exec, -1
	s_sub_i32 s24, s2, 0xf0
	s_addk_i32 s24, 0x1340
	v_lshrrev_b32_e32 v40, 5, v156
	v_and_b32_e32 v41, 31, v156
	v_lshlrev_b32_e32 v41, 4, v41
	v_mul_u32_u24_e32 v42, 0x204, v40
	v_add_u32_e32 v42, v42, v41
	v_and_b32_e32 v43, 7, v156
	v_mul_u32_u24_e32 v43, 0x1020, v43
	v_lshrrev_b32_e32 v51, 3, v156
	v_lshl_add_u32 v43, v51, 2, v43
	v_lshrrev_b32_e32 v44, 4, v51
	v_lshlrev_b32_e32 v44, 1, v44
	v_bfe_u32 v52, v156, 2, 1
	v_add_u32_e32 v44, v44, v52
	v_lshlrev_b32_e32 v44, 10, v44
	v_and_b32_e32 v52, 15, v51
	v_lshlrev_b32_e32 v52, 6, v52
	v_and_b32_e32 v53, 3, v156
	v_lshl_add_u32 v52, v53, 4, v52
	v_and_b32_e32 v53, 8, v51
	v_lshlrev_b32_e32 v53, 2, v53
	v_xor_b32_e32 v52, v52, v53
	v_add_u32_e32 v44, v44, v52
	v_add_u32_e32 v45, 0x2000, v44
	v_lshlrev_b32_e32 v50, 2, v40
	s_waitcnt lgkmcnt(0)
	s_cmpk_lt_i32 s24, 0x1340
	s_cbranch_scc0 .Lwd_down_p
	s_sub_i32 s25, s24, 0x840
	s_and_b32 s26, s25, 31
	s_lshr_b32 s27, s25, 5
	s_lshl_b32 s28, s26, 6
	s_and_b32 s29, s27, 1
	s_mul_i32 s29, s29, 0x1600
	s_lshr_b32 s30, s27, 1
	s_lshl_b32 s30, s30, 7
	s_add_i32 s29, s29, s30
	s_mul_i32 s30, s28, 0x2c00
	s_add_i32 s30, s30, s29
	s_lshl_b32 s30, s30, 2
	s_add_u32 s34, s18, s30
	s_addc_u32 s35, s19, 0
	s_lshl_b32 s31, s27, 5
	s_add_i32 s31, s31, s26
	s_mov_b32 s33, 0xb000
	s_mov_b32 s46, 1
	s_mov_b32 s30, 0x2100000
	s_branch .Lwd_dec_p

.Lwd_dec_p:
	s_lshl_b32 s31, s31, 14
	s_add_u32 s31, s31, s30
	s_add_u32 s44, s40, s31
	s_addc_u32 s45, s41, 0
	v_mul_lo_u32 v46, v40, s33
	v_add_u32_e32 v46, v46, v41
	s_lshl_b32 s30, s33, 4
	v_add_u32_e32 v47, s30, v46
	v_add_u32_e32 v48, s30, v47
	v_add_u32_e32 v49, s30, v48
	global_load_dwordx4 v[0:3], v46, s[34:35]
	global_load_dwordx4 v[4:7], v47, s[34:35]
	global_load_dwordx4 v[8:11], v48, s[34:35]
	global_load_dwordx4 v[12:15], v49, s[34:35]
	s_and_b32 s30, s28, 0x7ff
	s_lshl_b32 s30, s30, 2
	s_add_u32 s34, s20, s30
	s_addc_u32 s35, s21, 0
	global_load_dword v16, v50, s[34:35]
	global_load_dword v17, v50, s[34:35] offset:64
	global_load_dword v18, v50, s[34:35] offset:128
	global_load_dword v19, v50, s[34:35] offset:192
	s_addk_i32 s24, 0x10
	s_cmpk_lt_i32 s24, 0x1340
	s_cbranch_scc0 .Lwd_down_q
	s_sub_i32 s25, s24, 0x840
	s_and_b32 s26, s25, 31
	s_lshr_b32 s27, s25, 5
	s_lshl_b32 s28, s26, 6
	s_and_b32 s29, s27, 1
	s_mul_i32 s29, s29, 0x1600
	s_lshr_b32 s30, s27, 1
	s_lshl_b32 s30, s30, 7
	s_add_i32 s29, s29, s30
	s_mul_i32 s30, s28, 0x2c00
	s_add_i32 s30, s30, s29
	s_lshl_b32 s30, s30, 2
	s_add_u32 s34, s18, s30
	s_addc_u32 s35, s19, 0
	s_lshl_b32 s31, s27, 5
	s_add_i32 s31, s31, s26
	s_mov_b32 s33, 0xb000
	s_mov_b32 s47, 1
	s_mov_b32 s30, 0x2100000
	s_branch .Lwd_dec_q

.Lwd_loop:
	s_addk_i32 s24, 0x10
	s_cmpk_lt_i32 s24, 0x18c0
	s_cbranch_scc0 .Lwd_lastB
	s_cmpk_lt_i32 s24, 0x1340
	s_cbranch_scc0 .Lwd_down_r
	s_sub_i32 s25, s24, 0x840
	s_and_b32 s26, s25, 31
	s_lshr_b32 s27, s25, 5
	s_lshl_b32 s28, s26, 6
	s_and_b32 s29, s27, 1
	s_mul_i32 s29, s29, 0x1600
	s_lshr_b32 s30, s27, 1
	s_lshl_b32 s30, s30, 7
	s_add_i32 s29, s29, s30
	s_mul_i32 s30, s28, 0x2c00
	s_add_i32 s30, s30, s29
	s_lshl_b32 s30, s30, 2
	s_add_u32 s34, s18, s30
	s_addc_u32 s35, s19, 0
	s_lshl_b32 s31, s27, 5
	s_add_i32 s31, s31, s26
	s_mov_b32 s33, 0xb000
	s_mov_b32 s46, 1
	s_mov_b32 s30, 0x2100000
	s_branch .Lwd_dec_r

.Lwd_nog_b1:
	ds_write_b32 v42, v20
	ds_write_b32 v42, v21 offset:4
	ds_write_b32 v42, v22 offset:8
	ds_write_b32 v42, v23 offset:12
	ds_write_b32 v42, v24 offset:8256
	ds_write_b32 v42, v25 offset:8260
	ds_write_b32 v42, v26 offset:8264
	ds_write_b32 v42, v27 offset:8268
	ds_write_b32 v42, v28 offset:16512
	ds_write_b32 v42, v29 offset:16516
	ds_write_b32 v42, v30 offset:16520
	ds_write_b32 v42, v31 offset:16524
	ds_write_b32 v42, v32 offset:24768
	ds_write_b32 v42, v33 offset:24772
	ds_write_b32 v42, v34 offset:24776
	ds_write_b32 v42, v35 offset:24780
	s_waitcnt lgkmcnt(0)
	s_barrier
	ds_read_b32 v54, v43
	ds_read_b32 v55, v43 offset:516
	ds_read_b32 v56, v43 offset:1032
	ds_read_b32 v57, v43 offset:1548
	ds_read_b32 v58, v43 offset:2064
	ds_read_b32 v59, v43 offset:2580
	ds_read_b32 v60, v43 offset:3096
	ds_read_b32 v61, v43 offset:3612
	ds_read_b32 v62, v43 offset:256
	ds_read_b32 v63, v43 offset:772
	ds_read_b32 v64, v43 offset:1288
	ds_read_b32 v65, v43 offset:1804
	ds_read_b32 v66, v43 offset:2320
	ds_read_b32 v67, v43 offset:2836
	ds_read_b32 v68, v43 offset:3352
	ds_read_b32 v69, v43 offset:3868
	s_waitcnt lgkmcnt(0)
	v_cvt_pk_bf16_f32 v72, v54, v55
	v_cvt_pk_bf16_f32 v73, v56, v57
	v_cvt_pk_bf16_f32 v74, v58, v59
	v_cvt_pk_bf16_f32 v75, v60, v61
	v_cvt_pk_bf16_f32 v76, v62, v63
	v_cvt_pk_bf16_f32 v77, v64, v65
	v_cvt_pk_bf16_f32 v78, v66, v67
	v_cvt_pk_bf16_f32 v79, v68, v69
	global_store_dwordx4 v44, v[72:75], s[48:49]
	global_store_dwordx4 v45, v[76:79], s[48:49]
	s_barrier
	s_addk_i32 s24, 0x10
	s_cmpk_lt_i32 s24, 0x18c0
	s_cbranch_scc0 .Lwd_lastA
	s_cmpk_lt_i32 s24, 0x1340
	s_cbranch_scc0 .Lwd_down_s
	s_sub_i32 s25, s24, 0x840
	s_and_b32 s26, s25, 31
	s_lshr_b32 s27, s25, 5
	s_lshl_b32 s28, s26, 6
	s_and_b32 s29, s27, 1
	s_mul_i32 s29, s29, 0x1600
	s_lshr_b32 s30, s27, 1
	s_lshl_b32 s30, s30, 7
	s_add_i32 s29, s29, s30
	s_mul_i32 s30, s28, 0x2c00
	s_add_i32 s30, s30, s29
	s_lshl_b32 s30, s30, 2
	s_add_u32 s34, s18, s30
	s_addc_u32 s35, s19, 0
	s_lshl_b32 s31, s27, 5
	s_add_i32 s31, s31, s26
	s_mov_b32 s33, 0xb000
	s_mov_b32 s47, 1
	s_mov_b32 s30, 0x2100000
	s_branch .Lwd_dec_s

.Lwd_done:
	s_branch .Lwd_exit
.Lwd_exit:
	s_mov_b64 s[4:5], 0
